# attention L0: softmax bias LDS reads of the no-mask path hoisted (mb0/mb1 to the top of the key step, mb2 to its block start); no prefetch
# speedup vs baseline: 1.0059x; 1.0059x over previous
; #define LAS __attribute__((address_space(3)))
; __device__ __forceinline__ void attn_phase(const Params& p, LAS unsigned char* lds, int li, int tid, int G, bf16_t* __restrict__ dst, const bf16_t* __restrict__ ZGA) {
;     ...
;                 for (int ks = 0; ks < 4; ++ks)
; #pragma unroll
;                     for (int n = 0; n < 2; ++n) {
;                         const bf16x8 Kf = *(const LAS bf16x8*)(KS + (32 * qt + 16 * n + lq) * 256 + (((4 * ks + g) ^ lq) << 4));
; #pragma unroll
;                         for (int mb = 0; mb < 3; ++mb) sacc[mb][n] = __builtin_amdgcn_mfma_f32_16x16x32_bf16(Kf, Qf[mb][ks], sacc[mb][n], 0, 0, 0);
;                     }
;                 bf16x8 Pf[3];
; #pragma unroll
;                 for (int mb = 0; mb < 3; ++mb) {
;                     const int hh = mb, r = 16 * w + lq;
;                     u32x4 o = {0u, 0u, 0u, 0u};
;                     {
;                         const int ib = 128 * kb - r + 32 * qt + 4 * g;
;                         const LAS float* bh = BS + hh * 260;
;                         float ls = 0.f; float pe[2][4];
;                         if (nomask) {
; #pragma unroll
;                             for (int n = 0; n < 2; ++n)
; #pragma unroll
;                                 for (int j = 0; j < 4; ++j) { const float e = __builtin_amdgcn_exp2f(sacc[mb][n][j] + bh[ib + 16 * n + j]); pe[n][j] = e; ls += e; }
;                         } else {
; #pragma unroll
;                             for (int n = 0; n < 2; ++n)
; #pragma unroll
;                                 for (int j = 0; j < 4; ++j) {
;                                     const int idx = ib + 16 * n + j, ic = min(max(idx, 0), 256);
;                                     const float e = __builtin_amdgcn_exp2f(sacc[mb][n][j] + bh[ic]);
;                                     const float pv = (idx == ic) ? e : 0.f; pe[n][j] = pv; ls += pv;
;                                 }
;                         }
.LBB0_351:
.LBB0_352:
	v_add_u32_e32 v252, 0x20400, v189
	v_add_u32_e32 v253, 0x20810, v189
	ds_read2_b32 v[236:237], v252 offset1:1
	ds_read2_b32 v[238:239], v252 offset0:2 offset1:3
	ds_read2_b32 v[240:241], v252 offset0:16 offset1:17
	ds_read2_b32 v[242:243], v252 offset0:18 offset1:19
	ds_read2_b32 v[244:245], v253 offset1:1
	ds_read2_b32 v[246:247], v253 offset0:2 offset1:3
	ds_read2_b32 v[248:249], v253 offset0:16 offset1:17
	ds_read2_b32 v[250:251], v253 offset0:18 offset1:19
	v_add_u32_e32 v158, 0, v190
	ds_read_b128 v[146:149], v158
	v_add_u32_e32 v195, 0, v191
	ds_read_b128 v[196:199], v195
	ds_read_b128 v[158:161], v158 offset:4096
	v_add_u32_e32 v221, s0, v188
	v_add_u32_e32 v219, 1, v221
	s_mov_b64 s[64:65], -1
	s_and_b64 vcc, exec, s[4:5]
	v_med3_i32 v222, v221, 0, v203
	s_waitcnt lgkmcnt(0)
	v_mfma_f32_16x16x32_bf16 v[150:153], v[146:149], v[98:101], 0
	v_med3_i32 v220, v219, 0, v203
	v_mfma_f32_16x16x32_bf16 v[154:157], v[146:149], v[114:117], 0
	v_mfma_f32_16x16x32_bf16 v[146:149], v[146:149], v[130:133], 0
	v_mfma_f32_16x16x32_bf16 v[150:153], v[196:199], v[102:105], v[150:153]
	v_mfma_f32_16x16x32_bf16 v[154:157], v[196:199], v[118:121], v[154:157]
	v_mfma_f32_16x16x32_bf16 v[146:149], v[196:199], v[134:137], v[146:149]
	ds_read_b128 v[196:199], v195 offset:4096
	v_add_u32_e32 v195, 0, v192
	v_mfma_f32_16x16x32_bf16 v[162:165], v[158:161], v[98:101], 0
	v_mfma_f32_16x16x32_bf16 v[166:169], v[158:161], v[114:117], 0
	v_mfma_f32_16x16x32_bf16 v[158:161], v[158:161], v[130:133], 0
	s_waitcnt lgkmcnt(0)
	v_mfma_f32_16x16x32_bf16 v[162:165], v[196:199], v[102:105], v[162:165]
	v_mfma_f32_16x16x32_bf16 v[166:169], v[196:199], v[118:121], v[166:169]
	v_mfma_f32_16x16x32_bf16 v[158:161], v[196:199], v[134:137], v[158:161]
	ds_read_b128 v[196:199], v195
	s_waitcnt lgkmcnt(0)
	v_mfma_f32_16x16x32_bf16 v[150:153], v[196:199], v[106:109], v[150:153]
	v_mfma_f32_16x16x32_bf16 v[154:157], v[196:199], v[122:125], v[154:157]
	v_mfma_f32_16x16x32_bf16 v[146:149], v[196:199], v[138:141], v[146:149]
	ds_read_b128 v[196:199], v195 offset:4096
	v_add_u32_e32 v195, 0, v193
	s_waitcnt lgkmcnt(0)
	v_mfma_f32_16x16x32_bf16 v[210:213], v[196:199], v[106:109], v[162:165]
	v_mfma_f32_16x16x32_bf16 v[214:217], v[196:199], v[122:125], v[166:169]
	v_mfma_f32_16x16x32_bf16 v[196:199], v[196:199], v[138:141], v[158:161]
	s_nop 2
	ds_read_b128 v[158:161], v195
	s_waitcnt lgkmcnt(0)
	v_mfma_f32_16x16x32_bf16 v[166:169], v[158:161], v[110:113], v[150:153]
	v_mfma_f32_16x16x32_bf16 v[150:153], v[158:161], v[142:145], v[146:149]
	s_nop 2
	ds_read_b128 v[146:149], v195 offset:4096
	v_mfma_f32_16x16x32_bf16 v[162:165], v[158:161], v[126:129], v[154:157]
	v_add_u32_e32 v195, 19, v221
	s_waitcnt lgkmcnt(0)
	v_mfma_f32_16x16x32_bf16 v[154:157], v[146:149], v[110:113], v[210:213]
	s_nop 2
	v_add_u32_e32 v213, 16, v221
	v_add_u32_e32 v211, 17, v221
	v_med3_i32 v212, v211, 0, v203
	v_mfma_f32_16x16x32_bf16 v[158:161], v[146:149], v[126:129], v[214:217]
	v_mfma_f32_16x16x32_bf16 v[146:149], v[146:149], v[142:145], v[196:199]
	s_nop 1
	v_add_u32_e32 v217, 2, v221
	v_add_u32_e32 v215, 3, v221
	v_med3_i32 v218, v217, 0, v203
	v_add_u32_e32 v199, 18, v221
	v_med3_i32 v216, v215, 0, v203
	v_med3_i32 v214, v213, 0, v203
	v_med3_i32 v210, v199, 0, v203
	v_med3_i32 v197, v195, 0, v203
	s_cbranch_vccnz .LBB0_354
	s_add_i32 s19, 0, 0x20400
	v_lshl_add_u32 v196, v222, 2, s19
	v_lshl_add_u32 v198, v220, 2, s19
	v_lshl_add_u32 v223, v218, 2, s19
	v_lshl_add_u32 v224, v216, 2, s19
	v_lshl_add_u32 v225, v214, 2, s19
	v_lshl_add_u32 v226, v212, 2, s19
	v_lshl_add_u32 v227, v210, 2, s19
	v_lshl_add_u32 v228, v197, 2, s19
	ds_read_b32 v196, v196
	ds_read_b32 v198, v198
	ds_read_b32 v229, v223
	ds_read_b32 v230, v224
	ds_read_b32 v231, v225
	ds_read_b32 v232, v226
	ds_read_b32 v233, v227
	ds_read_b32 v234, v228
	s_waitcnt lgkmcnt(0)
	v_add_f32_e32 v196, v166, v196
	v_exp_f32_e32 v196, v196
	v_add_f32_e32 v198, v167, v198
	v_exp_f32_e32 v198, v198
	v_cmp_eq_u32_e32 vcc, v221, v222
	v_add_f32_e32 v225, v169, v230
	v_exp_f32_e32 v226, v225
	v_cndmask_b32_e32 v223, 0, v196, vcc
	v_cmp_eq_u32_e32 vcc, v219, v220
	v_add_f32_e32 v227, v155, v232
	v_add_f32_e32 v196, 0, v223
	v_cndmask_b32_e32 v224, 0, v198, vcc
	v_add_f32_e32 v198, v168, v229
	v_exp_f32_e32 v198, v198
	v_cmp_eq_u32_e32 vcc, v217, v218
	v_exp_f32_e32 v228, v227
	v_add_f32_e32 v196, v196, v224
	v_cndmask_b32_e32 v225, 0, v198, vcc
	v_add_f32_e32 v198, v154, v231
	v_exp_f32_e32 v198, v198
	v_cmp_eq_u32_e32 vcc, v215, v216
	v_add_f32_e32 v229, v157, v234
	v_add_f32_e32 v196, v196, v225
	v_cndmask_b32_e32 v226, 0, v226, vcc
	v_cmp_eq_u32_e32 vcc, v213, v214
	v_exp_f32_e32 v230, v229
	v_add_f32_e32 v196, v196, v226
	v_cndmask_b32_e32 v227, 0, v198, vcc
	v_add_f32_e32 v198, v156, v233
	v_exp_f32_e32 v198, v198
	v_cmp_eq_u32_e32 vcc, v211, v212
	v_add_f32_e32 v196, v196, v227
	s_mov_b64 s[64:65], 0
	v_cndmask_b32_e32 v228, 0, v228, vcc
	v_cmp_eq_u32_e32 vcc, v199, v210
	v_add_f32_e32 v196, v196, v228
	s_nop 0
	v_cndmask_b32_e32 v229, 0, v198, vcc
	v_cmp_eq_u32_e32 vcc, v195, v197
	v_add_f32_e32 v196, v196, v229
	s_nop 0
	v_cndmask_b32_e32 v230, 0, v230, vcc
	v_add_f32_e32 v198, v196, v230
.LBB0_354:
	s_andn2_b64 vcc, exec, s[64:65]
	v_add_u32_e32 v196, 0, v189
	s_cbranch_vccnz .LBB0_356
	s_waitcnt lgkmcnt(0)
	v_add_f32_e32 v166, v166, v236
	v_exp_f32_e32 v223, v166
	v_add_f32_e32 v167, v167, v237
	v_exp_f32_e32 v224, v167
	v_add_f32_e32 v166, 0, v223
	v_add_f32_e32 v198, v166, v224
	v_add_f32_e32 v166, v168, v238
	v_exp_f32_e32 v225, v166
	v_add_f32_e32 v167, v169, v239
	v_exp_f32_e32 v226, v167
	v_add_f32_e32 v166, v198, v225
	v_add_f32_e32 v168, v166, v226
	v_add_f32_e32 v154, v154, v240
	v_exp_f32_e32 v227, v154
	v_add_f32_e32 v155, v155, v241
	v_exp_f32_e32 v228, v155
	v_add_f32_e32 v154, v168, v227
	v_add_f32_e32 v166, v154, v228
	v_add_f32_e32 v154, v156, v242
	v_exp_f32_e32 v229, v154
	v_add_f32_e32 v155, v157, v243
	v_exp_f32_e32 v230, v155
	v_add_f32_e32 v154, v166, v229
	v_add_f32_e32 v198, v154, v230

; __device__ __forceinline__ void attn_phase(const Params& p, LAS unsigned char* lds, int li, int tid, int G, bf16_t* __restrict__ dst, const bf16_t* __restrict__ ZGA) {
;     ...
;                         if (nomask) {
; #pragma unroll
;                             for (int n = 0; n < 2; ++n)
; #pragma unroll
;                                 for (int j = 0; j < 4; ++j) { const float e = __builtin_amdgcn_exp2f(sacc[mb][n][j] + bh[ib + 16 * n + j]); pe[n][j] = e; ls += e; }
.LBB0_358:
	s_andn2_b64 vcc, exec, s[64:65]
	s_cbranch_vccnz .LBB0_360
	s_waitcnt lgkmcnt(0)
	v_add_f32_e32 v162, v162, v244
	v_exp_f32_e32 v167, v162
	v_add_f32_e32 v163, v163, v245
	v_exp_f32_e32 v168, v163
	v_add_f32_e32 v162, 0, v167
	v_add_f32_e32 v166, v162, v168
	v_add_f32_e32 v162, v164, v246
	v_exp_f32_e32 v169, v162
	v_add_f32_e32 v163, v165, v247
	v_exp_f32_e32 v223, v163
	v_add_f32_e32 v162, v166, v169
	v_add_f32_e32 v164, v162, v223
	v_add_f32_e32 v158, v158, v248
	v_exp_f32_e32 v224, v158
	v_add_f32_e32 v159, v159, v249
	v_exp_f32_e32 v225, v159
	v_add_f32_e32 v158, v164, v224
	v_add_f32_e32 v162, v158, v225
	v_add_f32_e32 v158, v160, v250
	v_exp_f32_e32 v226, v158
	v_add_f32_e32 v159, v161, v251
	v_exp_f32_e32 v227, v159
	v_add_f32_e32 v158, v162, v226
	v_add_f32_e32 v166, v158, v227

; __device__ __forceinline__ void attn_phase(const Params& p, LAS unsigned char* lds, int li, int tid, int G, bf16_t* __restrict__ dst, const bf16_t* __restrict__ ZGA) {
;     ...
;                         if (nomask) {
; #pragma unroll
;                             for (int n = 0; n < 2; ++n)
; #pragma unroll
;                                 for (int j = 0; j < 4; ++j) { const float e = __builtin_amdgcn_exp2f(sacc[mb][n][j] + bh[ib + 16 * n + j]); pe[n][j] = e; ls += e; }
.LBB0_362:
	s_andn2_b64 vcc, exec, s[4:5]
	s_cbranch_vccnz .LBB0_332
	v_add_u32_e32 v253, 0x20c20, v196
	ds_read2_b32 v[236:237], v253 offset1:1
	ds_read2_b32 v[238:239], v253 offset0:2 offset1:3
	ds_read2_b32 v[240:241], v253 offset0:16 offset1:17
	ds_read2_b32 v[242:243], v253 offset0:18 offset1:19
	s_waitcnt lgkmcnt(0)
	v_add_f32_e32 v150, v150, v236
	v_exp_f32_e32 v162, v150
	v_add_f32_e32 v151, v151, v237
	v_exp_f32_e32 v163, v151
	v_add_f32_e32 v150, 0, v162
	v_add_f32_e32 v165, v150, v163
	v_add_f32_e32 v150, v152, v238
	v_exp_f32_e32 v164, v150
	v_add_f32_e32 v151, v153, v239
	v_add_f32_e32 v150, v165, v164
	v_exp_f32_e32 v165, v151
	s_nop 0
	v_add_f32_e32 v152, v150, v165
	v_add_f32_e32 v146, v146, v240
	v_exp_f32_e32 v167, v146
	v_add_f32_e32 v147, v147, v241
	v_exp_f32_e32 v168, v147
	v_add_f32_e32 v146, v152, v167
	v_add_f32_e32 v150, v146, v168
	v_add_f32_e32 v146, v148, v242
	v_exp_f32_e32 v169, v146
	v_add_f32_e32 v147, v149, v243
	v_exp_f32_e32 v223, v147
	v_add_f32_e32 v146, v150, v169
	v_add_f32_e32 v224, v146, v223
	s_branch .LBB0_332
